# unit setup: back-to-back reloads of the same workspace pointer (each followed by a full wait) collapsed to one load plus register copies
# speedup vs baseline: 1.0038x; 1.0009x over previous
.LBB0_506:
	s_cmpk_gt_i32 s6, 0x8f
	s_mov_b64 s[8:9], -1
	s_cbranch_scc0 .LBB0_600
	s_cmpk_gt_u32 s6, 0x28f
	s_cbranch_scc0 .LBB0_571
	s_cmpk_gt_u32 s6, 0x48f
	s_cbranch_scc0 .LBB0_528
	v_readlane_b32 s8, v254, 49
	v_readlane_b32 s9, v254, 50
	s_andn2_b64 vcc, exec, s[8:9]
	s_cbranch_vccnz .LBB0_527
	v_mov_b32_e32 v2, s64
	v_mov_b32_e32 v3, s65
	v_mov_b32_e32 v4, s64
	v_readfirstlane_b32 s7, v2
	v_readfirstlane_b32 s8, v3
	v_mov_b32_e32 v5, s65
	v_mov_b32_e32 v2, s7
	v_mov_b32_e32 v3, s8
	global_load_dwordx2 v[2:3], v[2:3], off offset:248
	s_waitcnt vmcnt(0) lgkmcnt(0)
	v_mov_b32_e32 v0, s64
	v_readfirstlane_b32 s7, v4
	v_readfirstlane_b32 s8, v5
	v_mov_b32_e32 v6, s65
	v_mov_b32_e32 v4, s7
	v_mov_b32_e32 v5, s8
	v_mov_b32_e32 v4, v2
	v_mov_b32_e32 v5, v3
	s_waitcnt vmcnt(0) lgkmcnt(0)
	s_add_i32 s15, s6, 0xfffffb70
	v_readfirstlane_b32 s7, v0
	v_readfirstlane_b32 s8, v6
	s_lshr_b32 s18, s15, 1
	v_mov_b32_e32 v6, s7
	v_mov_b32_e32 v7, s8
	v_mov_b32_e32 v6, v2
	v_mov_b32_e32 v7, v3
	s_bfe_u32 s7, s15, 0x20001
	s_lshr_b32 s21, s15, 6
	s_cmp_lt_u32 s15, 64
	v_mov_b32_e32 v18, v247
	s_cselect_b64 s[40:41], -1, 0
	s_cmp_gt_u32 s15, 63
	v_readfirstlane_b32 s26, v2
	v_readfirstlane_b32 s27, v3
	v_readfirstlane_b32 s12, v4
	v_readfirstlane_b32 s13, v5
	s_mov_b64 s[24:25], -1
	s_waitcnt vmcnt(0) lgkmcnt(0)
	v_mov_b32_e32 v0, v7
	s_nop 0
	v_readfirstlane_b32 s8, v6
	v_readfirstlane_b32 s9, v0
	s_cbranch_scc0 .LBB0_516
	s_lshl_b32 s28, s7, 6
	s_cmp_lg_u32 s21, 1
	s_cbranch_scc0 .LBB0_513
	s_lshl_b32 s14, s18, 5
	s_and_b32 s23, s14, 64
	s_add_i32 s22, s28, 0x380
	s_or_b32 s14, s23, 0x480
	s_or_b32 s23, s23, 0x180
	s_mov_b64 s[24:25], 0

.LBB0_528:
	s_andn2_b64 vcc, exec, s[8:9]
	s_cbranch_vccnz .LBB0_570
	v_mov_b32_e32 v2, s64
	v_mov_b32_e32 v3, s65
	v_mov_b32_e32 v4, s64
	v_readfirstlane_b32 s7, v2
	v_readfirstlane_b32 s8, v3
	v_mov_b32_e32 v5, s65
	v_mov_b32_e32 v2, s7
	v_mov_b32_e32 v3, s8
	global_load_dwordx2 v[2:3], v[2:3], off offset:248
	s_waitcnt vmcnt(0) lgkmcnt(0)
	v_mov_b32_e32 v21, v247
	v_readfirstlane_b32 s7, v4
	v_readfirstlane_b32 s8, v5
	v_readfirstlane_b32 s12, v3
	v_mov_b32_e32 v4, s7
	v_mov_b32_e32 v5, s8
	v_mov_b32_e32 v12, v2
	v_mov_b32_e32 v13, v3
	v_mov_b32_e32 v4, s64
	v_mov_b32_e32 v5, s65
	s_waitcnt vmcnt(0) lgkmcnt(0)
	s_mov_b32 s9, s19
	v_readfirstlane_b32 s7, v4
	v_readfirstlane_b32 s8, v5
	v_mov_b32_e32 v71, v1
	v_mov_b32_e32 v4, s7
	v_mov_b32_e32 v5, s8
	v_mov_b32_e32 v28, v2
	v_mov_b32_e32 v29, v3
	s_add_i32 s7, s6, 0xfffffd70
	v_readfirstlane_b32 s8, v2
	s_add_u32 s22, s8, 0x9f00000
	s_addc_u32 s23, s12, 0
	s_bfe_u32 s21, s7, 0x20004
	s_lshr_b32 s14, s7, 6
	s_lshl_b32 s7, s7, 1
	s_and_b32 s24, s7, 30
	s_lshl_b32 s8, s14, 11
	v_mov_b64_e32 v[2:3], s[22:23]
	s_lshl_b32 s18, s21, 7
	v_mov_b32_e32 v0, s64
	v_mov_b32_e32 v14, s65
	v_readfirstlane_b32 s15, v13
	v_sub_u32_e64 v32, s24, 3 clamp
	s_waitcnt vmcnt(0) lgkmcnt(0)
	v_mov_b32_e32 v20, v29
	v_mov_b32_e32 v13, s15
	v_ashrrev_i32_e32 v22, 8, v21
	v_lshrrev_b32_e32 v4, 1, v21
	v_add_u32_e32 v25, s24, v22
	v_and_b32_e32 v5, 24, v4
	v_lshlrev_b32_e32 v4, 6, v25
	v_lshrrev_b32_e32 v26, 2, v21
	v_lshlrev_b32_e32 v70, 1, v5
	v_ashrrev_i32_e32 v5, 31, v4
	v_and_b32_e32 v23, 15, v21
	v_and_b32_e32 v24, 48, v26
	v_lshl_add_u64 v[68:69], v[4:5], 0, s[8:9]
	v_or3_b32 v68, v68, v24, v23
	v_mad_u64_u32 v[4:5], s[12:13], v68, s2, v[2:3]
	v_mad_i32_i24 v5, v69, s2, v5
	v_lshl_add_u64 v[4:5], v[4:5], 0, s[18:19]
	v_lshl_add_u64 v[8:9], v[4:5], 0, v[70:71]
	global_load_dwordx4 v[4:7], v[8:9], off offset:768
	s_nop 0
	global_load_dwordx4 v[8:11], v[8:9], off offset:832
	v_ashrrev_i32_e32 v72, 3, v21
	v_readfirstlane_b32 s7, v0
	v_readfirstlane_b32 s9, v14
	s_mov_b32 s13, s19
	v_mov_b32_e32 v14, s7
	v_mov_b32_e32 v15, s9
	global_load_dwordx2 v[30:31], v[14:15], off offset:112
	s_lshl_b32 s7, s21, 6
	s_lshl_b32 s9, s14, 8
	s_add_i32 s14, s7, 0x80
	s_add_i32 s12, s9, 0x4000
	v_readfirstlane_b32 s9, v12
	v_ashrrev_i32_e32 v73, 31, v72
	v_add_u32_e32 v16, s14, v72
	v_mov_b32_e32 v12, s9
	v_lshl_add_u64 v[14:15], v[72:73], 0, s[12:13]
	s_mov_b32 s9, 0x9000
	v_mad_i64_i32 v[12:13], s[14:15], v16, s9, v[12:13]
	v_mad_u64_u32 v[16:17], s[14:15], v14, s2, v[2:3]
	v_lshlrev_b32_e32 v27, 3, v21
	s_mov_b64 s[14:15], 0x17700000
	v_mad_i32_i24 v17, v15, s2, v17
	v_and_b32_e32 v71, 56, v27
	v_lshl_add_u64 v[2:3], v[12:13], 0, s[14:15]
	v_lshl_add_u64 v[12:13], v[16:17], 0, s[18:19]
	s_lshl_b32 s18, s12, 1
	v_lshlrev_b32_e32 v0, 1, v71
	v_lshl_add_u64 v[14:15], v[2:3], 0, s[18:19]
	v_lshl_add_u64 v[12:13], v[12:13], 0, v[0:1]
	v_lshl_add_u64 v[16:17], v[14:15], 0, v[0:1]
	v_readfirstlane_b32 s12, v32
	s_min_u32 s12, s12, 24
	v_readfirstlane_b32 s13, v20
	v_lshlrev_b32_e32 v20, 4, v21
	s_movk_i32 s18, 0x90
	v_and_b32_e32 v27, 32, v27
	v_and_b32_e32 v20, 16, v20
	s_mov_b64 s[14:15], -1
	v_and_b32_e32 v98, 12, v26
	s_waitcnt vmcnt(0) lgkmcnt(0)
	v_mov_b32_e32 v29, v30
	global_load_dwordx4 v[12:15], v[12:13], off offset:1280
	s_nop 0
	global_load_dwordx4 v[16:19], v[16:17], off
	v_sub_u32_e64 v30, s24, 4 clamp
	v_readfirstlane_b32 s24, v31
	v_readfirstlane_b32 s9, v30
	s_min_u32 s9, s9, 24
	s_sub_i32 s9, s12, s9
	v_readfirstlane_b32 s12, v28
	v_lshlrev_b32_e32 v28, 1, v21
	v_and_b32_e32 v28, 4, v28
	v_mul_lo_u32 v30, v72, s18
	s_add_i32 s9, s9, 8
	v_or3_b32 v96, v27, v20, v28
	v_add_u32_e32 v97, 16, v30
	v_add_u32_e32 v20, v97, v0
	v_lshl_add_u32 v27, v96, 1, v97
	s_cmp_gt_i32 s9, -4
	v_readfirstlane_b32 s18, v29
	v_add_u32_e32 v27, 0x2000, v27
	s_waitcnt vmcnt(0) lgkmcnt(0)
	ds_write_b128 v20, v[12:15]
	ds_write2_b64 v27, v[16:17], v[18:19] offset0:128 offset1:130
	s_waitcnt lgkmcnt(0)
	s_barrier
	s_cbranch_scc1 .LBB0_531
	v_and_b32_e32 v20, 12, v26
	s_mov_b64 s[14:15], 0

.LBB0_571:
	s_andn2_b64 vcc, exec, s[8:9]
	s_cbranch_vccnz .LBB0_599
	v_mov_b32_e32 v2, s64
	v_mov_b32_e32 v3, s65
	v_mov_b32_e32 v0, s64
	v_readfirstlane_b32 s7, v2
	v_readfirstlane_b32 s8, v3
	v_mov_b32_e32 v8, s65
	v_mov_b32_e32 v2, s7
	v_mov_b32_e32 v3, s8
	global_load_dwordx2 v[4:5], v[2:3], off offset:248
	v_mov_b32_e32 v2, s64
	v_mov_b32_e32 v3, s65
	s_waitcnt vmcnt(0) lgkmcnt(0)
	v_mov_b32_e32 v22, v247
	v_readfirstlane_b32 s7, v2
	v_readfirstlane_b32 s8, v3
	v_readfirstlane_b32 s12, v5
	v_mov_b32_e32 v2, s7
	v_mov_b32_e32 v3, s8
	global_load_dwordx2 v[6:7], v[2:3], off offset:248
	s_waitcnt vmcnt(0) lgkmcnt(0)
	s_mov_b32 s13, s19
	v_readfirstlane_b32 s7, v0
	v_readfirstlane_b32 s8, v8
	v_readfirstlane_b32 s25, v6
	v_mov_b32_e32 v2, s7
	v_mov_b32_e32 v3, s8
	v_mov_b32_e32 v2, v6
	v_mov_b32_e32 v3, v7
	s_add_i32 s8, s6, 0xffffff70
	v_readfirstlane_b32 s7, v4
	s_add_u32 s22, s7, 0x9f00000
	s_addc_u32 s23, s12, 0
	s_lshr_b32 s18, s8, 6
	s_lshl_b32 s12, s8, 7
	s_lshl_b32 s24, s8, 1
	s_and_b32 s21, s12, 0x780
	s_lshl_b32 s12, s18, 8
	s_lshl_b64 s[14:15], s[18:19], 11
	s_and_b32 s24, s24, 64
	s_add_i32 s18, s12, 0x4000
	v_readfirstlane_b32 s26, v7
	v_mov_b64_e32 v[4:5], s[22:23]
	s_lshl_b32 s12, s24, 1
	v_mov_b32_e32 v6, s25
	v_mov_b32_e32 v7, s26
	s_bfe_u32 s7, s8, 0x20004
	s_mov_b32 s9, s19
	s_lshl_b32 s8, s7, 7
	v_mov_b32_e32 v69, v1
	s_movk_i32 s26, 0x90
	s_waitcnt vmcnt(0) lgkmcnt(0)
	v_mov_b32_e32 v25, v3
	s_nop 0
	v_ashrrev_i32_e32 v0, 2, v22
	v_ashrrev_i32_e32 v70, 3, v22
	v_lshrrev_b32_e32 v8, 1, v22
	v_and_b32_e32 v23, -16, v0
	v_ashrrev_i32_e32 v71, 31, v70
	v_and_b32_e32 v3, 15, v22
	v_and_b32_e32 v0, 24, v8
	v_add_u32_e32 v10, s24, v70
	v_add_u32_e32 v24, s21, v23
	v_lshl_add_u64 v[8:9], v[70:71], 0, s[18:19]
	s_mov_b32 s24, 0x9000
	v_mad_i64_i32 v[6:7], s[24:25], v10, s24, v[6:7]
	v_or_b32_e32 v10, v24, v3
	v_mad_u64_u32 v[12:13], s[24:25], v8, s2, v[4:5]
	v_lshlrev_b32_e32 v26, 3, v22
	s_mov_b64 s[24:25], 0x17700000
	v_ashrrev_i32_e32 v11, 31, v10
	v_and_b32_e32 v78, 56, v26
	s_lshl_b32 s18, s18, 1
	v_lshl_add_u64 v[20:21], v[6:7], 0, s[24:25]
	v_lshl_add_u64 v[72:73], s[14:15], 0, v[10:11]
	v_lshlrev_b32_e32 v68, 1, v0
	v_lshlrev_b32_e32 v0, 1, v78
	v_mad_i32_i24 v13, v9, s2, v13
	v_lshl_add_u64 v[6:7], v[20:21], 0, s[18:19]
	v_mad_u64_u32 v[4:5], s[24:25], v72, s2, v[4:5]
	v_lshl_add_u64 v[8:9], v[12:13], 0, s[12:13]
	v_lshl_add_u64 v[6:7], v[6:7], 0, v[0:1]
	v_mad_i32_i24 v5, v73, s2, v5
	v_lshl_add_u64 v[8:9], v[8:9], 0, v[0:1]
	global_load_dwordx4 v[16:19], v[6:7], off
	global_load_dwordx4 v[12:15], v[8:9], off offset:512
	v_lshl_add_u64 v[4:5], v[4:5], 0, s[8:9]
	v_lshl_add_u64 v[8:9], v[4:5], 0, v[68:69]
	global_load_dwordx4 v[4:7], v[8:9], off
	s_nop 0
	global_load_dwordx4 v[8:11], v[8:9], off offset:64
	s_max_u32 s13, s21, 0x80
	s_min_u32 s8, s21, 0x700
	s_sub_i32 s18, s8, s13
	v_readfirstlane_b32 s8, v2
	v_readfirstlane_b32 s9, v25
	v_lshlrev_b32_e32 v2, 4, v22
	v_lshlrev_b32_e32 v25, 1, v22
	v_and_b32_e32 v26, 32, v26
	v_and_b32_e32 v2, 16, v2
	v_and_b32_e32 v25, 4, v25
	v_mul_lo_u32 v27, v70, s26
	v_or3_b32 v69, v26, v2, v25
	v_add_u32_e32 v79, 16, v27
	v_lshl_add_u32 v25, v69, 1, v79
	s_addk_i32 s18, 0x180
	v_add_u32_e32 v2, v79, v0
	v_add_u32_e32 v25, 0x2000, v25
	s_ashr_i32 s21, s18, 6
	s_mov_b64 s[24:25], -1
	s_cmp_gt_i32 s21, -4
	s_waitcnt vmcnt(0) lgkmcnt(0)
	ds_write2_b64 v25, v[16:17], v[18:19] offset0:128 offset1:130
	ds_write_b128 v2, v[12:15]
	v_lshrrev_b32_e32 v2, 2, v22
	v_and_b32_e32 v80, 12, v2
	s_waitcnt lgkmcnt(0)
	s_barrier
	s_cbranch_scc1 .LBB0_574
	v_and_b32_e32 v22, 12, v2
	s_mov_b64 s[24:25], 0

.LBB0_629:
	s_cmpk_gt_i32 s4, 0x1ff
	s_cbranch_scc0 .LBB0_648
	s_cmpk_gt_u32 s4, 0x3ff
	s_cbranch_scc0 .LBB0_649
	v_readlane_b32 s8, v254, 49
	v_readlane_b32 s9, v254, 50
	s_mov_b64 s[6:7], 0
	s_and_b64 vcc, exec, s[8:9]
	s_mov_b64 s[8:9], 0
	s_cbranch_vccz .LBB0_650
	v_mov_b32_e32 v2, s64
	v_mov_b32_e32 v3, s65
	v_mov_b32_e32 v4, s64
	v_readfirstlane_b32 s8, v2
	v_readfirstlane_b32 s9, v3
	v_mov_b32_e32 v5, s65
	v_mov_b32_e32 v2, s8
	v_mov_b32_e32 v3, s9
	global_load_dwordx2 v[2:3], v[2:3], off offset:248
	s_waitcnt vmcnt(0) lgkmcnt(0)
	v_mov_b32_e32 v0, s64
	v_readfirstlane_b32 s8, v4
	v_readfirstlane_b32 s9, v5
	v_mov_b32_e32 v6, s65
	v_mov_b32_e32 v4, s8
	v_mov_b32_e32 v5, s9
	v_mov_b32_e32 v4, v2
	v_mov_b32_e32 v5, v3
	s_waitcnt vmcnt(0) lgkmcnt(0)
	s_add_i32 s15, s4, 0xfffffc00
	v_readfirstlane_b32 s8, v0
	v_readfirstlane_b32 s9, v6
	s_lshr_b32 s18, s15, 1
	v_mov_b32_e32 v6, s8
	v_mov_b32_e32 v7, s9
	v_mov_b32_e32 v6, v2
	v_mov_b32_e32 v7, v3
	s_bfe_u32 s26, s15, 0x20001
	s_lshr_b32 s27, s15, 6
	s_cmp_lt_u32 s15, 64
	v_mov_b32_e32 v56, v247
	s_cselect_b64 s[40:41], -1, 0
	s_cmp_gt_u32 s15, 63
	v_readfirstlane_b32 s28, v2
	v_readfirstlane_b32 s29, v3
	v_readfirstlane_b32 s12, v4
	v_readfirstlane_b32 s13, v5
	s_mov_b64 s[24:25], -1
	s_waitcnt vmcnt(0) lgkmcnt(0)
	v_mov_b32_e32 v0, v7
	s_nop 0
	v_readfirstlane_b32 s8, v6
	v_readfirstlane_b32 s9, v0
	s_cbranch_scc0 .LBB0_638
	s_lshl_b32 s30, s26, 6
	s_cmp_lg_u32 s27, 1
	s_cbranch_scc0 .LBB0_635
	s_lshl_b32 s14, s18, 5
	s_and_b32 s23, s14, 64
	s_add_i32 s22, s30, 0x380
	s_or_b32 s14, s23, 0x480
	s_or_b32 s23, s23, 0x180
	s_mov_b64 s[24:25], 0

.LBB0_651:
	v_mov_b32_e32 v2, s64
	v_mov_b32_e32 v3, s65
	v_mov_b32_e32 v4, s64
	v_readfirstlane_b32 s6, v2
	v_readfirstlane_b32 s7, v3
	v_mov_b32_e32 v5, s65
	v_mov_b32_e32 v2, s6
	v_mov_b32_e32 v3, s7
	global_load_dwordx2 v[2:3], v[2:3], off offset:248
	s_waitcnt vmcnt(0) lgkmcnt(0)
	v_mov_b32_e32 v71, v1
	v_readfirstlane_b32 s6, v4
	v_readfirstlane_b32 s7, v5
	v_readfirstlane_b32 s8, v2
	v_mov_b32_e32 v4, s6
	v_mov_b32_e32 v5, s7
	v_mov_b32_e32 v10, v2
	v_mov_b32_e32 v11, v3
	v_mov_b32_e32 v4, s64
	v_mov_b32_e32 v5, s65
	s_waitcnt vmcnt(0) lgkmcnt(0)
	v_readfirstlane_b32 s9, v3
	v_readfirstlane_b32 s6, v4
	v_readfirstlane_b32 s7, v5
	v_mov_b32_e32 v0, s64
	v_mov_b32_e32 v4, s6
	s_add_i32 s6, s4, 0xfffffe00
	v_mov_b32_e32 v5, s7
	s_add_u32 s14, s8, 0x9f00000
	v_mov_b32_e32 v12, v2
	v_mov_b32_e32 v13, v3
	v_mov_b32_e32 v4, v247
	s_addc_u32 s15, s9, 0
	s_lshr_b32 s12, s6, 6
	s_lshl_b32 s6, s6, 1
	s_and_b32 s23, s6, 30
	s_waitcnt vmcnt(0) lgkmcnt(0)
	s_mov_b32 s7, s19
	v_ashrrev_i32_e32 v5, 8, v4
	v_lshrrev_b32_e32 v14, 1, v4
	v_add_u32_e32 v8, s23, v5
	v_and_b32_e32 v15, 24, v14
	v_lshlrev_b32_e32 v14, 6, v8
	s_lshl_b32 s6, s12, 11
	v_lshrrev_b32_e32 v9, 2, v4
	v_lshlrev_b32_e32 v70, 1, v15
	v_ashrrev_i32_e32 v15, 31, v14
	v_and_b32_e32 v6, 15, v4
	v_and_b32_e32 v7, 48, v9
	v_lshl_add_u64 v[68:69], v[14:15], 0, s[6:7]
	v_mov_b64_e32 v[2:3], s[14:15]
	v_or3_b32 v68, v68, v7, v6
	s_bfe_u32 s22, s4, 0x20004
	v_mad_u64_u32 v[14:15], s[8:9], v68, s2, v[2:3]
	s_lshl_b32 s18, s22, 7
	v_mad_i32_i24 v15, v69, s2, v15
	v_lshl_add_u64 v[14:15], v[14:15], 0, s[18:19]
	v_mov_b32_e32 v16, s65
	v_lshl_add_u64 v[14:15], v[14:15], 0, v[70:71]
	global_load_dwordx4 v[20:23], v[14:15], off offset:768
	global_load_dwordx4 v[24:27], v[14:15], off offset:832
	v_ashrrev_i32_e32 v72, 3, v4
	v_readfirstlane_b32 s7, v0
	v_readfirstlane_b32 s8, v16
	s_mov_b32 s9, s19
	v_mov_b32_e32 v14, s7
	v_mov_b32_e32 v15, s8
	s_lshl_b32 s7, s22, 6
	s_lshl_b32 s8, s12, 8
	s_add_i32 s12, s7, 0x80
	s_addk_i32 s8, 0x4000
	v_readfirstlane_b32 s13, v10
	v_readfirstlane_b32 s24, v11
	v_ashrrev_i32_e32 v73, 31, v72
	v_mov_b32_e32 v10, s13
	v_mov_b32_e32 v11, s24
	v_add_u32_e32 v18, s12, v72
	v_lshl_add_u64 v[16:17], v[72:73], 0, s[8:9]
	s_mov_b32 s9, 0x9000
	v_lshlrev_b32_e32 v36, 3, v4
	v_mad_i64_i32 v[10:11], s[12:13], v18, s9, v[10:11]
	v_mad_u64_u32 v[18:19], s[12:13], v16, s2, v[2:3]
	v_and_b32_e32 v71, 56, v36
	s_mov_b64 s[12:13], 0x17700000
	v_mad_i32_i24 v19, v17, s2, v19
	v_lshlrev_b32_e32 v0, 1, v71
	v_lshl_add_u64 v[2:3], v[10:11], 0, s[12:13]
	v_lshl_add_u64 v[10:11], v[18:19], 0, s[18:19]
	s_lshl_b32 s18, s8, 1
	global_load_dwordx2 v[14:15], v[14:15], off offset:112
	v_lshl_add_u64 v[10:11], v[10:11], 0, v[0:1]
	v_lshl_add_u64 v[16:17], v[2:3], 0, s[18:19]
	v_lshl_add_u64 v[16:17], v[16:17], 0, v[0:1]
	s_waitcnt vmcnt(0) lgkmcnt(0)
	global_load_dwordx4 v[28:31], v[10:11], off offset:1280
	global_load_dwordx4 v[32:35], v[16:17], off
	v_sub_u32_e64 v10, s23, 4 clamp
	v_sub_u32_e64 v11, s23, 3 clamp
	v_readfirstlane_b32 s8, v10
	v_readfirstlane_b32 s9, v11
	s_min_u32 s8, s8, 24
	s_min_u32 s9, s9, 24
	v_lshlrev_b32_e32 v10, 4, v4
	v_lshlrev_b32_e32 v11, 1, v4
	s_movk_i32 s18, 0x90
	s_sub_i32 s51, s9, s8
	v_readfirstlane_b32 s8, v12
	v_readfirstlane_b32 s9, v13
	v_and_b32_e32 v12, 32, v36
	v_and_b32_e32 v10, 16, v10
	v_and_b32_e32 v11, 4, v11
	v_mul_lo_u32 v13, v72, s18
	s_add_i32 s51, s51, 8
	v_or3_b32 v96, v12, v10, v11
	v_add_u32_e32 v97, 16, v13
	s_mov_b64 s[12:13], -1
	v_add_u32_e32 v10, v97, v0
	v_lshl_add_u32 v11, v96, 1, v97
	s_cmp_gt_i32 s51, -4
	v_readfirstlane_b32 s18, v14
	v_readfirstlane_b32 s23, v15
	v_and_b32_e32 v98, 12, v9
	v_add_u32_e32 v11, 0x2000, v11
	s_waitcnt vmcnt(0) lgkmcnt(0)
	ds_write_b128 v10, v[28:31]
	ds_write2_b64 v11, v[32:33], v[34:35] offset0:128 offset1:130
	s_waitcnt lgkmcnt(0)
	s_barrier
	s_cbranch_scc1 .LBB0_653
	v_and_b32_e32 v36, 12, v9
	s_mov_b64 s[12:13], 0

.LBB0_694:
	v_mov_b32_e32 v2, s64
	v_mov_b32_e32 v3, s65
	v_mov_b32_e32 v4, s64
	v_readfirstlane_b32 s6, v2
	v_readfirstlane_b32 s7, v3
	v_mov_b32_e32 v5, s65
	v_mov_b32_e32 v2, s6
	v_mov_b32_e32 v3, s7
	global_load_dwordx2 v[2:3], v[2:3], off offset:248
	s_waitcnt vmcnt(0) lgkmcnt(0)
	v_mov_b32_e32 v0, s64
	v_readfirstlane_b32 s6, v4
	v_readfirstlane_b32 s7, v5
	v_mov_b32_e32 v6, s65
	v_mov_b32_e32 v4, s6
	v_mov_b32_e32 v5, s7
	v_mov_b32_e32 v4, v2
	v_mov_b32_e32 v5, v3
	s_waitcnt vmcnt(0) lgkmcnt(0)
	v_mov_b32_e32 v71, v1
	v_readfirstlane_b32 s6, v0
	v_readfirstlane_b32 s7, v6
	v_readfirstlane_b32 s15, v4
	v_mov_b32_e32 v6, s6
	v_readfirstlane_b32 s6, v2
	v_mov_b32_e32 v7, s7
	v_readfirstlane_b32 s7, v3
	s_add_u32 s8, s6, 0x9f00000
	s_addc_u32 s9, s7, 0
	s_ashr_i32 s6, s4, 6
	s_lshl_b32 s7, s4, 7
	s_lshl_b32 s12, s4, 1
	s_and_b32 s14, s7, 0x780
	s_ashr_i32 s7, s6, 31
	s_and_b32 s26, s12, 64
	s_lshl_b32 s23, s6, 8
	s_lshl_b64 s[12:13], s[6:7], 11
	s_max_u32 s27, s14, 0x80
	s_min_u32 s6, s14, 0x700
	s_bfe_u32 s22, s4, 0x20004
	s_sub_i32 s25, s6, s27
	v_mov_b32_e32 v8, v2
	v_mov_b32_e32 v9, v3
	v_mov_b32_e32 v7, v247
	s_lshl_b32 s18, s22, 7
	s_ashr_i32 s24, s23, 31
	s_addk_i32 s25, 0x180
	s_add_u32 s6, s23, 0x4000
	s_waitcnt vmcnt(0) lgkmcnt(0)
	s_addc_u32 s7, s24, 0
	v_ashrrev_i32_e32 v0, 2, v7
	v_ashrrev_i32_e32 v72, 3, v7
	v_readfirstlane_b32 s28, v5
	v_and_b32_e32 v5, -16, v0
	v_ashrrev_i32_e32 v73, 31, v72
	v_mov_b64_e32 v[10:11], s[8:9]
	v_mov_b32_e32 v2, s15
	v_mov_b32_e32 v3, s28
	v_and_b32_e32 v4, 15, v7
	v_add_u32_e32 v14, s26, v72
	v_add_u32_e32 v6, s14, v5
	v_lshl_add_u64 v[12:13], s[6:7], 0, v[72:73]
	s_mov_b32 s14, 0x9000
	v_mad_i64_i32 v[2:3], s[14:15], v14, s14, v[2:3]
	v_or_b32_e32 v14, v6, v4
	v_mad_u64_u32 v[16:17], s[14:15], v12, s2, v[10:11]
	s_mov_b64 s[14:15], 0x17700000
	v_ashrrev_i32_e32 v15, 31, v14
	v_lshlrev_b32_e32 v19, 3, v7
	v_lshl_add_u64 v[2:3], v[2:3], 0, s[14:15]
	v_lshl_add_u64 v[68:69], s[12:13], 0, v[14:15]
	v_and_b32_e32 v78, 56, v19
	v_mad_i32_i24 v17, v13, s2, v17
	v_lshl_add_u64 v[12:13], s[6:7], 1, v[2:3]
	v_mad_u64_u32 v[10:11], s[6:7], v68, s2, v[10:11]
	v_lshlrev_b32_e32 v0, 1, v78
	v_mad_i32_i24 v11, v69, s2, v11
	v_lshl_add_u64 v[12:13], v[12:13], 0, v[0:1]
	v_lshl_add_u64 v[10:11], v[10:11], 0, s[18:19]
	s_lshl_b32 s18, s26, 1
	global_load_dwordx4 v[28:31], v[12:13], off
	v_lshl_add_u64 v[12:13], v[16:17], 0, s[18:19]
	v_lshrrev_b32_e32 v18, 1, v7
	v_lshl_add_u64 v[12:13], v[12:13], 0, v[0:1]
	global_load_dwordx4 v[32:35], v[12:13], off offset:512
	v_and_b32_e32 v12, 24, v18
	v_lshlrev_b32_e32 v70, 1, v12
	v_lshl_add_u64 v[10:11], v[10:11], 0, v[70:71]
	global_load_dwordx4 v[20:23], v[10:11], off
	global_load_dwordx4 v[24:27], v[10:11], off offset:64
	v_readfirstlane_b32 s6, v8
	v_readfirstlane_b32 s7, v9
	v_lshlrev_b32_e32 v8, 4, v7
	v_lshlrev_b32_e32 v9, 1, v7
	s_movk_i32 s28, 0x90
	v_and_b32_e32 v10, 32, v19
	v_and_b32_e32 v8, 16, v8
	v_and_b32_e32 v9, 4, v9
	v_mul_lo_u32 v11, v72, s28
	v_or3_b32 v71, v10, v8, v9
	v_add_u32_e32 v79, 16, v11
	s_ashr_i32 s26, s25, 6
	v_lshrrev_b32_e32 v7, 2, v7
	v_lshl_add_u32 v9, v71, 1, v79
	s_mov_b64 s[14:15], -1
	v_add_u32_e32 v9, 0x2000, v9
	s_cmp_gt_i32 s26, -4
	v_and_b32_e32 v80, 12, v7
	v_add_u32_e32 v8, v79, v0
	s_waitcnt vmcnt(0) lgkmcnt(0)
	ds_write2_b64 v9, v[28:29], v[30:31] offset0:128 offset1:130
	ds_write_b128 v8, v[32:35]
	s_waitcnt lgkmcnt(0)
	s_barrier
	s_cbranch_scc1 .LBB0_696
	v_and_b32_e32 v36, 12, v7
	s_mov_b64 s[14:15], 0

.LBB0_824:
	s_cmpk_gt_i32 s8, 0x8f
	s_mov_b64 s[6:7], -1
	s_cbranch_scc0 .LBB0_834
	v_mov_b32_e32 v2, s64
	v_mov_b32_e32 v3, s65
	v_mov_b32_e32 v4, s64
	v_readfirstlane_b32 s0, v2
	v_readfirstlane_b32 s1, v3
	v_mov_b32_e32 v5, s65
	v_mov_b32_e32 v2, s0
	v_mov_b32_e32 v3, s1
	global_load_dwordx2 v[2:3], v[2:3], off offset:248
	s_waitcnt vmcnt(0) lgkmcnt(0)
	v_mov_b32_e32 v0, s64
	v_readfirstlane_b32 s0, v4
	v_readfirstlane_b32 s1, v5
	v_mov_b32_e32 v6, s65
	v_mov_b32_e32 v4, s0
	v_mov_b32_e32 v5, s1
	v_mov_b32_e32 v4, v2
	v_mov_b32_e32 v5, v3
	v_readfirstlane_b32 s4, v3
	v_mov_b32_e32 v32, v247
	s_mov_b32 s23, s19
	s_mov_b32 s13, s19
	v_mov_b32_e32 v31, v1
	v_cmp_lt_i32_e32 vcc, v222, v220
	v_mov_b32_e32 v68, 0xf149f2ca
	v_mov_b32_e32 v62, 0
	s_waitcnt vmcnt(0) lgkmcnt(0)
	v_mov_b32_e32 v8, v5
	s_nop 0
	v_readfirstlane_b32 s0, v0
	v_readfirstlane_b32 s1, v6
	v_readfirstlane_b32 s9, v4
	v_mov_b32_e32 v6, s0
	v_mov_b32_e32 v7, s1
	s_add_i32 s0, s8, 0xffffff70
	v_readfirstlane_b32 s1, v2
	s_add_u32 s14, s1, 0x9f00000
	v_mov_b32_e32 v50, v2
	v_mov_b32_e32 v51, v3
	s_addc_u32 s15, s4, 0
	s_lshl_b32 s1, s0, 7
	s_bfe_u32 s4, s0, 0x20004
	s_lshr_b32 s18, s0, 6
	s_lshl_b32 s0, s0, 1
	s_and_b32 s1, s1, 0x780
	s_waitcnt vmcnt(0) lgkmcnt(0)
	s_lshl_b64 s[6:7], s[18:19], 11
	v_ashrrev_i32_e32 v0, 2, v32
	v_and_b32_e32 v33, 15, v32
	s_and_b32 s5, s0, 64
	s_lshl_b32 s0, s18, 8
	v_readfirstlane_b32 s20, v8
	v_lshrrev_b32_e32 v4, 1, v32
	v_ashrrev_i32_e32 v54, 3, v32
	v_and_b32_e32 v8, -16, v0
	v_or_b32_e32 v0, s1, v33
	v_mov_b32_e32 v5, s7
	s_add_i32 s18, s0, 0x4000
	v_and_b32_e32 v52, 24, v4
	v_ashrrev_i32_e32 v55, 31, v54
	v_add_u32_e32 v12, s5, v54
	v_ashrrev_i32_e32 v9, 31, v8
	v_or_b32_e32 v4, s6, v0
	v_mov_b64_e32 v[2:3], s[14:15]
	v_mov_b32_e32 v6, s9
	v_mov_b32_e32 v7, s20
	v_lshl_add_u64 v[10:11], s[18:19], 0, v[54:55]
	v_add_u32_e32 v12, 0x180, v12
	v_lshl_add_u64 v[56:57], v[4:5], 0, v[8:9]
	v_lshlrev_b32_e32 v36, 3, v32
	v_mad_u64_u32 v[4:5], s[20:21], v10, s2, v[2:3]
	v_mad_i64_i32 v[6:7], s[20:21], v12, s33, v[6:7]
	v_mad_u64_u32 v[2:3], s[20:21], v56, s2, v[2:3]
	s_lshl_b32 s22, s4, 7
	s_lshl_b32 s12, s5, 1
	v_and_b32_e32 v53, 56, v36
	v_mad_i32_i24 v5, v11, s2, v5
	s_mov_b64 s[20:21], 0x17700000
	v_mad_i32_i24 v3, v57, s2, v3
	v_lshlrev_b32_e32 v0, 1, v52
	v_lshlrev_b32_e32 v30, 1, v53
	v_lshl_add_u64 v[34:35], v[6:7], 0, s[20:21]
	v_lshl_add_u64 v[4:5], v[4:5], 0, s[12:13]
	v_lshl_add_u64 v[2:3], v[2:3], 0, s[22:23]
	v_lshl_add_u64 v[6:7], s[18:19], 1, v[34:35]
	v_lshl_add_u64 v[4:5], v[4:5], 0, v[30:31]
	v_lshl_add_u64 v[2:3], v[2:3], 0, v[0:1]
	v_lshl_add_u64 v[6:7], v[6:7], 0, v[30:31]
	global_load_dwordx4 v[22:25], v[4:5], off offset:2304
	global_load_dwordx4 v[26:29], v[6:7], off
	global_load_dwordx4 v[14:17], v[2:3], off offset:1792
	global_load_dwordx4 v[18:21], v[2:3], off offset:1856
	v_lshlrev_b32_e32 v37, 4, v32
	v_lshlrev_b32_e32 v32, 1, v32
	s_movk_i32 s9, 0x90
	v_cndmask_b32_e32 v6, v219, v222, vcc
	v_cmp_lt_i32_e32 vcc, v221, v220
	v_and_b32_e32 v36, 32, v36
	v_and_b32_e32 v37, 16, v37
	v_and_b32_e32 v32, 4, v32
	v_mul_lo_u32 v38, v54, s9
	v_cndmask_b32_e32 v7, v219, v221, vcc
	v_mov_b32_e32 v4, v1
	v_mov_b32_e32 v5, v1
	v_mul_u32_u24_e32 v65, 0x90, v33
	v_or3_b32 v66, v36, v37, v32
	v_add_u32_e32 v67, 16, v38
	v_lshl_add_u64 v[32:33], s[14:15], 0, v[30:31]
	s_or_b32 s18, s12, 0x900
	v_mov_b32_e32 v2, v1
	v_mov_b32_e32 v3, v1
	v_lshlrev_b32_e32 v64, 2, v6
	v_lshlrev_b32_e32 v63, 2, v7
	v_mov_b64_e32 v[8:9], v[4:5]
	v_mov_b64_e32 v[12:13], v[4:5]
	v_add_u32_e32 v36, v67, v30
	v_lshl_add_u64 v[58:59], v[34:35], 0, v[30:31]
	v_lshl_add_u64 v[60:61], v[32:33], 0, s[18:19]
	v_mov_b64_e32 v[32:33], v[4:5]
	s_mov_b32 s1, 0
	s_movk_i32 s5, 0x4040
	v_mov_b64_e32 v[6:7], v[2:3]
	v_mov_b64_e32 v[10:11], v[2:3]
	s_lshl_b32 s4, s4, 6
	v_lshl_add_u32 v37, v66, 1, v67
	v_mov_b64_e32 v[30:31], v[2:3]
	v_add_u32_e32 v37, 0x2000, v37
	s_waitcnt vmcnt(0) lgkmcnt(0)
	ds_write_b128 v36, v[22:25]
	ds_write2_b64 v37, v[26:27], v[28:29] offset0:128 offset1:130
	s_waitcnt lgkmcnt(0)
	s_barrier
	s_branch .LBB0_827

.LBB0_883:
	s_andn2_b64 vcc, exec, s[6:7]
	s_cbranch_vccnz .LBB0_979
	s_cmpk_gt_i32 s40, 0x8f
	s_cbranch_scc0 .LBB0_893
	s_branch .Lga_entry
	v_mov_b32_e32 v2, s64
	v_mov_b32_e32 v3, s65
	v_mov_b32_e32 v4, s64
	v_readfirstlane_b32 s0, v2
	v_readfirstlane_b32 s1, v3
	v_mov_b32_e32 v5, s65
	v_mov_b32_e32 v2, s0
	v_mov_b32_e32 v3, s1
	global_load_dwordx2 v[2:3], v[2:3], off offset:248
	s_waitcnt vmcnt(0) lgkmcnt(0)
	v_mov_b32_e32 v0, s64
	v_readfirstlane_b32 s0, v4
	v_readfirstlane_b32 s1, v5
	v_mov_b32_e32 v6, s65
	v_mov_b32_e32 v4, s0
	v_mov_b32_e32 v5, s1
	v_mov_b32_e32 v4, v2
	v_mov_b32_e32 v5, v3
	v_mov_b32_e32 v32, v247
	s_mov_b32 s15, s19
	s_mov_b32 s9, s19
	v_mov_b32_e32 v31, v1
	v_cmp_lt_i32_e32 vcc, v222, v220
	v_mov_b32_e32 v68, 0xf149f2ca
	v_mov_b32_e32 v64, 0
	s_waitcnt vmcnt(0) lgkmcnt(0)
	v_mov_b32_e32 v8, v5
	s_nop 0
	v_readfirstlane_b32 s0, v0
	v_readfirstlane_b32 s1, v6
	v_readfirstlane_b32 s20, v4
	v_mov_b32_e32 v6, s0
	v_readfirstlane_b32 s0, v2
	v_mov_b32_e32 v7, s1
	v_readfirstlane_b32 s1, v3
	s_add_u32 s12, s0, 0x9f00000
	v_mov_b32_e32 v50, v2
	v_mov_b32_e32 v51, v3
	s_addc_u32 s13, s1, 0
	s_lshl_b32 s0, s40, 7
	s_lshr_b32 s18, s40, 6
	s_lshl_b32 s1, s40, 1
	s_and_b32 s0, s0, 0x780
	s_waitcnt vmcnt(0) lgkmcnt(0)
	s_lshl_b64 s[6:7], s[18:19], 11
	v_ashrrev_i32_e32 v0, 2, v32
	v_and_b32_e32 v33, 15, v32
	s_and_b32 s4, s1, 64
	s_lshl_b32 s1, s18, 8
	v_readfirstlane_b32 s21, v8
	v_lshrrev_b32_e32 v4, 1, v32
	v_ashrrev_i32_e32 v54, 3, v32
	v_and_b32_e32 v8, -16, v0
	v_or_b32_e32 v0, s0, v33
	v_mov_b32_e32 v5, s7
	s_add_i32 s18, s1, 0x4000
	v_and_b32_e32 v52, 24, v4
	v_ashrrev_i32_e32 v55, 31, v54
	v_add_u32_e32 v12, s4, v54
	v_ashrrev_i32_e32 v9, 31, v8
	v_or_b32_e32 v4, s6, v0
	v_mov_b64_e32 v[2:3], s[12:13]
	v_mov_b32_e32 v6, s20
	v_mov_b32_e32 v7, s21
	v_lshl_add_u64 v[10:11], s[18:19], 0, v[54:55]
	v_add_u32_e32 v12, 0x180, v12
	v_lshl_add_u64 v[56:57], v[4:5], 0, v[8:9]
	s_bfe_u32 s5, s40, 0x20004
	v_lshlrev_b32_e32 v36, 3, v32
	v_mad_u64_u32 v[4:5], s[20:21], v10, s2, v[2:3]
	v_mad_i64_i32 v[6:7], s[20:21], v12, s33, v[6:7]
	v_mad_u64_u32 v[2:3], s[20:21], v56, s2, v[2:3]
	s_lshl_b32 s14, s5, 7
	s_lshl_b32 s8, s4, 1
	v_and_b32_e32 v53, 56, v36
	v_mad_i32_i24 v5, v11, s2, v5
	s_mov_b64 s[20:21], 0x17700000
	v_mad_i32_i24 v3, v57, s2, v3
	v_lshlrev_b32_e32 v0, 1, v52
	v_lshlrev_b32_e32 v30, 1, v53
	v_lshl_add_u64 v[34:35], v[6:7], 0, s[20:21]
	v_lshl_add_u64 v[4:5], v[4:5], 0, s[8:9]
	v_lshl_add_u64 v[2:3], v[2:3], 0, s[14:15]
	v_lshl_add_u64 v[6:7], s[18:19], 1, v[34:35]
	v_lshl_add_u64 v[4:5], v[4:5], 0, v[30:31]
	v_lshl_add_u64 v[2:3], v[2:3], 0, v[0:1]
	v_lshl_add_u64 v[6:7], v[6:7], 0, v[30:31]
	global_load_dwordx4 v[22:25], v[4:5], off offset:2304
	global_load_dwordx4 v[26:29], v[6:7], off
	global_load_dwordx4 v[14:17], v[2:3], off offset:1792
	global_load_dwordx4 v[18:21], v[2:3], off offset:1856
	v_lshlrev_b32_e32 v37, 4, v32
	v_lshlrev_b32_e32 v32, 1, v32
	s_movk_i32 s9, 0x90
	v_cndmask_b32_e32 v6, v219, v222, vcc
	v_cmp_lt_i32_e32 vcc, v221, v220
	v_and_b32_e32 v36, 32, v36
	v_and_b32_e32 v37, 16, v37
	v_and_b32_e32 v32, 4, v32
	v_mul_lo_u32 v38, v54, s9
	v_cndmask_b32_e32 v7, v219, v221, vcc
	v_mov_b32_e32 v4, v1
	v_mov_b32_e32 v5, v1
	v_mul_u32_u24_e32 v65, 0x90, v33
	v_or3_b32 v66, v36, v37, v32
	v_add_u32_e32 v67, 16, v38
	v_lshl_add_u64 v[32:33], s[12:13], 0, v[30:31]
	s_or_b32 s18, s8, 0x900
	v_mov_b32_e32 v2, v1
	v_mov_b32_e32 v3, v1
	v_lshlrev_b32_e32 v63, 2, v6
	v_lshlrev_b32_e32 v62, 2, v7
	v_mov_b64_e32 v[8:9], v[4:5]
	v_mov_b64_e32 v[12:13], v[4:5]
	v_add_u32_e32 v36, v67, v30
	v_lshl_add_u64 v[58:59], v[34:35], 0, v[30:31]
	v_lshl_add_u64 v[60:61], v[32:33], 0, s[18:19]
	v_mov_b64_e32 v[32:33], v[4:5]
	s_mov_b32 s4, 0
	s_movk_i32 s14, 0x4040
	v_mov_b64_e32 v[6:7], v[2:3]
	v_mov_b64_e32 v[10:11], v[2:3]
	s_lshl_b32 s5, s5, 6
	v_lshl_add_u32 v37, v66, 1, v67
	v_mov_b64_e32 v[30:31], v[2:3]
	v_add_u32_e32 v37, 0x2000, v37
	s_waitcnt vmcnt(0) lgkmcnt(0)
	ds_write_b128 v36, v[22:25]
	ds_write2_b64 v37, v[26:27], v[28:29] offset0:128 offset1:130
	s_waitcnt lgkmcnt(0)
	s_barrier
	s_branch .LBB0_887

.LBB0_894:
	ds_bpermute_b32 v0, v63, v64
	s_lshl_b32 s18, s5, 1
	v_readfirstlane_b32 s6, v50
	v_readfirstlane_b32 s7, v51
	v_lshlrev_b64 v[14:15], 11, v[56:57]
	s_waitcnt lgkmcnt(0)
	v_add_f32_e32 v0, v64, v0
	ds_bpermute_b32 v16, v62, v0
	v_lshl_add_u64 v[14:15], s[6:7], 0, v[14:15]
	v_mov_b32_e32 v53, v1
	v_lshl_add_u64 v[14:15], v[14:15], 0, s[18:19]
	v_lshl_add_u64 v[14:15], v[14:15], 0, v[52:53]
	s_waitcnt lgkmcnt(0)
	v_add_f32_e32 v0, v0, v16
	v_div_scale_f32 v16, s[4:5], v0, v0, 1.0
	v_rcp_f32_e32 v17, v16
	v_div_scale_f32 v18, vcc, 1.0, v0, 1.0
	s_mov_b64 s[4:5], 0x1e300400
	v_fma_f32 v19, -v16, v17, 1.0
	v_fmac_f32_e32 v17, v19, v17
	v_mul_f32_e32 v19, v18, v17
	v_fma_f32 v20, -v16, v19, v18
	v_fmac_f32_e32 v19, v20, v17
	v_fma_f32 v16, -v16, v19, v18
	v_div_fmas_f32 v16, v16, v17, v19
	v_div_fixup_f32 v0, v16, v0, 1.0
	v_pk_mul_f32 v[2:3], v[2:3], v[0:1] op_sel_hi:[1,0]
	v_pk_mul_f32 v[4:5], v[4:5], v[0:1] op_sel_hi:[1,0]
	v_lshl_add_u64 v[16:17], v[14:15], 0, s[4:5]
	v_pk_mul_f32 v[18:19], v[30:31], v[0:1] op_sel_hi:[1,0]
	v_pk_mul_f32 v[20:21], v[32:33], v[0:1] op_sel_hi:[1,0]
	v_add_co_u32_e32 v14, vcc, s34, v14
	v_pk_mul_f32 v[10:11], v[10:11], v[0:1] op_sel_hi:[1,0]
	v_pk_mul_f32 v[12:13], v[12:13], v[0:1] op_sel_hi:[1,0]
	v_pk_mul_f32 v[6:7], v[6:7], v[0:1] op_sel_hi:[1,0]
	v_pk_mul_f32 v[8:9], v[8:9], v[0:1] op_sel_hi:[1,0]
	v_cvt_pk_bf16_f32 v2, v2, v3
	v_cvt_pk_bf16_f32 v3, v4, v5
	v_cvt_pk_bf16_f32 v18, v18, v19
	v_cvt_pk_bf16_f32 v19, v20, v21
	v_addc_co_u32_e32 v15, vcc, 0, v15, vcc
	v_cvt_pk_bf16_f32 v10, v10, v11
	v_cvt_pk_bf16_f32 v11, v12, v13
	v_cvt_pk_bf16_f32 v6, v6, v7
	v_cvt_pk_bf16_f32 v7, v8, v9
	global_store_dwordx2 v[16:17], v[2:3], off offset:96
	v_mov_b32_e32 v2, s65
	v_mov_b32_e32 v3, s64
	global_store_dwordx2 v[14:15], v[18:19], off offset:1024
	global_store_dwordx2 v[16:17], v[10:11], off offset:32
	global_store_dwordx2 v[16:17], v[6:7], off offset:64
	v_mov_b32_e32 v4, s65
	v_readfirstlane_b32 s1, v3
	v_readfirstlane_b32 s4, v2
	v_mov_b32_e32 v5, s64
	v_mov_b32_e32 v2, s1
	v_mov_b32_e32 v3, s4
	global_load_dwordx2 v[2:3], v[2:3], off offset:248
	s_waitcnt vmcnt(0) lgkmcnt(0)
	v_mov_b32_e32 v0, s64
	v_readfirstlane_b32 s1, v5
	v_readfirstlane_b32 s4, v4
	v_mov_b32_e32 v6, s65
	v_mov_b32_e32 v4, s1
	v_mov_b32_e32 v5, s4
	v_mov_b32_e32 v4, v2
	v_mov_b32_e32 v5, v3
	s_waitcnt vmcnt(0) lgkmcnt(0)
	v_mov_b32_e32 v34, v247
	v_readfirstlane_b32 s1, v0
	v_readfirstlane_b32 s4, v6
	v_readfirstlane_b32 s5, v3
	v_mov_b32_e32 v6, s1
	v_mov_b32_e32 v7, s4
	v_mov_b32_e32 v50, v2
	v_mov_b32_e32 v51, v3
	s_add_i32 s1, s40, 0x70
	v_readfirstlane_b32 s4, v2
	s_add_u32 s12, s4, 0x9f00000
	s_addc_u32 s13, s5, 0
	s_bfe_u32 s5, s1, 0x20004
	s_lshr_b32 s18, s1, 6
	s_lshl_b32 s1, s1, 1
	s_lshl_b64 s[6:7], s[18:19], 11
	s_and_b32 s4, s1, 64
	s_lshl_b32 s1, s18, 8
	v_mov_b32_e32 v7, s7
	s_add_i32 s18, s1, 0x4000
	v_readfirstlane_b32 s20, v4
	v_readfirstlane_b32 s21, v5
	v_mov_b64_e32 v[2:3], s[12:13]
	v_mov_b32_e32 v4, s20
	v_mov_b32_e32 v5, s21
	s_mov_b32 s15, s19
	s_mov_b32 s9, s19
	s_lshl_b32 s14, s5, 7
	s_lshl_b32 s8, s4, 1
	v_mov_b32_e32 v31, v1
	v_mov_b32_e32 v68, 0xf149f2ca
	v_mov_b32_e32 v64, 0
	s_lshl_b32 s5, s5, 6
	s_waitcnt vmcnt(0) lgkmcnt(0)
	v_mov_b32_e32 v60, v50
	s_nop 0
	v_ashrrev_i32_e32 v0, 2, v34
	v_and_b32_e32 v35, 15, v34
	v_lshrrev_b32_e32 v6, 1, v34
	v_ashrrev_i32_e32 v52, 3, v34
	v_and_b32_e32 v8, -16, v0
	v_or_b32_e32 v0, s0, v35
	v_and_b32_e32 v50, 24, v6
	v_ashrrev_i32_e32 v53, 31, v52
	v_add_u32_e32 v12, s4, v52
	v_ashrrev_i32_e32 v9, 31, v8
	v_or_b32_e32 v6, s6, v0
	v_lshl_add_u64 v[10:11], s[18:19], 0, v[52:53]
	v_add_u32_e32 v12, 0x180, v12
	v_lshl_add_u64 v[54:55], v[6:7], 0, v[8:9]
	v_lshlrev_b32_e32 v36, 3, v34
	v_mad_u64_u32 v[6:7], s[20:21], v10, s2, v[2:3]
	v_mad_i64_i32 v[4:5], s[20:21], v12, s33, v[4:5]
	v_mad_u64_u32 v[2:3], s[20:21], v54, s2, v[2:3]
	v_and_b32_e32 v61, 56, v36
	v_mad_i32_i24 v7, v11, s2, v7
	s_mov_b64 s[20:21], 0x17700000
	v_mad_i32_i24 v3, v55, s2, v3
	v_lshlrev_b32_e32 v0, 1, v50
	v_lshlrev_b32_e32 v30, 1, v61
	v_lshl_add_u64 v[32:33], v[4:5], 0, s[20:21]
	v_lshl_add_u64 v[4:5], v[6:7], 0, s[8:9]
	v_lshl_add_u64 v[2:3], v[2:3], 0, s[14:15]
	v_lshl_add_u64 v[6:7], s[18:19], 1, v[32:33]
	v_lshl_add_u64 v[4:5], v[4:5], 0, v[30:31]
	v_lshl_add_u64 v[2:3], v[2:3], 0, v[0:1]
	v_lshl_add_u64 v[6:7], v[6:7], 0, v[30:31]
	global_load_dwordx4 v[22:25], v[4:5], off offset:2304
	global_load_dwordx4 v[26:29], v[6:7], off
	global_load_dwordx4 v[14:17], v[2:3], off offset:1792
	global_load_dwordx4 v[18:21], v[2:3], off offset:1856
	s_movk_i32 s9, 0x90
	v_lshlrev_b32_e32 v37, 4, v34
	v_lshlrev_b32_e32 v34, 1, v34
	v_mul_lo_u32 v38, v52, s9
	v_mov_b32_e32 v4, v1
	v_mov_b32_e32 v5, v1
	v_and_b32_e32 v36, 32, v36
	v_and_b32_e32 v37, 16, v37
	v_and_b32_e32 v34, 4, v34
	v_add_u32_e32 v67, 16, v38
	v_mov_b32_e32 v2, v1
	v_mov_b32_e32 v3, v1
	v_mov_b64_e32 v[8:9], v[4:5]
	v_mov_b64_e32 v[12:13], v[4:5]
	v_mul_u32_u24_e32 v65, 0x90, v35
	v_or3_b32 v66, v36, v37, v34
	v_add_u32_e32 v36, v67, v30
	v_lshl_add_u64 v[34:35], s[12:13], 0, v[30:31]
	v_lshl_add_u64 v[56:57], v[32:33], 0, v[30:31]
	s_or_b32 s18, s8, 0x900
	v_mov_b64_e32 v[32:33], v[4:5]
	s_mov_b32 s4, 0
	s_movk_i32 s14, 0x4040
	v_mov_b64_e32 v[6:7], v[2:3]
	v_mov_b64_e32 v[10:11], v[2:3]
	v_lshl_add_u32 v37, v66, 1, v67
	v_lshl_add_u64 v[58:59], v[34:35], 0, s[18:19]
	v_mov_b64_e32 v[30:31], v[2:3]
	v_add_u32_e32 v37, 0x2000, v37
	s_waitcnt vmcnt(0) lgkmcnt(0)
	ds_write_b128 v36, v[22:25]
	ds_write2_b64 v37, v[26:27], v[28:29] offset0:128 offset1:130
	s_waitcnt lgkmcnt(0)
	s_barrier
	s_branch .LBB0_896

.LBB0_902:
	ds_bpermute_b32 v0, v63, v64
	s_lshl_b32 s18, s5, 1
	v_readfirstlane_b32 s6, v60
	v_readfirstlane_b32 s7, v51
	v_lshlrev_b64 v[14:15], 11, v[54:55]
	s_waitcnt lgkmcnt(0)
	v_add_f32_e32 v0, v64, v0
	ds_bpermute_b32 v16, v62, v0
	v_lshl_add_u64 v[14:15], s[6:7], 0, v[14:15]
	v_mov_b32_e32 v51, v1
	v_lshl_add_u64 v[14:15], v[14:15], 0, s[18:19]
	v_lshl_add_u64 v[14:15], v[14:15], 0, v[50:51]
	s_waitcnt lgkmcnt(0)
	v_add_f32_e32 v0, v0, v16
	v_div_scale_f32 v16, s[4:5], v0, v0, 1.0
	v_rcp_f32_e32 v17, v16
	v_div_scale_f32 v18, vcc, 1.0, v0, 1.0
	s_mov_b64 s[4:5], 0x1e300400
	v_fma_f32 v19, -v16, v17, 1.0
	v_fmac_f32_e32 v17, v19, v17
	v_mul_f32_e32 v19, v18, v17
	v_fma_f32 v20, -v16, v19, v18
	v_fmac_f32_e32 v19, v20, v17
	v_fma_f32 v16, -v16, v19, v18
	v_div_fmas_f32 v16, v16, v17, v19
	v_div_fixup_f32 v0, v16, v0, 1.0
	v_pk_mul_f32 v[2:3], v[2:3], v[0:1] op_sel_hi:[1,0]
	v_pk_mul_f32 v[4:5], v[4:5], v[0:1] op_sel_hi:[1,0]
	v_lshl_add_u64 v[16:17], v[14:15], 0, s[4:5]
	v_pk_mul_f32 v[18:19], v[30:31], v[0:1] op_sel_hi:[1,0]
	v_pk_mul_f32 v[20:21], v[32:33], v[0:1] op_sel_hi:[1,0]
	v_add_co_u32_e32 v14, vcc, s34, v14
	v_pk_mul_f32 v[10:11], v[10:11], v[0:1] op_sel_hi:[1,0]
	v_pk_mul_f32 v[12:13], v[12:13], v[0:1] op_sel_hi:[1,0]
	v_pk_mul_f32 v[6:7], v[6:7], v[0:1] op_sel_hi:[1,0]
	v_pk_mul_f32 v[8:9], v[8:9], v[0:1] op_sel_hi:[1,0]
	v_cvt_pk_bf16_f32 v2, v2, v3
	v_cvt_pk_bf16_f32 v3, v4, v5
	v_cvt_pk_bf16_f32 v18, v18, v19
	v_cvt_pk_bf16_f32 v19, v20, v21
	v_addc_co_u32_e32 v15, vcc, 0, v15, vcc
	v_cvt_pk_bf16_f32 v10, v10, v11
	v_cvt_pk_bf16_f32 v11, v12, v13
	v_cvt_pk_bf16_f32 v6, v6, v7
	v_cvt_pk_bf16_f32 v7, v8, v9
	global_store_dwordx2 v[16:17], v[2:3], off offset:96
	v_mov_b32_e32 v2, s64
	v_mov_b32_e32 v3, s65
	global_store_dwordx2 v[14:15], v[18:19], off offset:1024
	global_store_dwordx2 v[16:17], v[10:11], off offset:32
	global_store_dwordx2 v[16:17], v[6:7], off offset:64
	v_mov_b32_e32 v4, s64
	v_readfirstlane_b32 s1, v2
	v_readfirstlane_b32 s4, v3
	v_mov_b32_e32 v5, s65
	v_mov_b32_e32 v2, s1
	v_mov_b32_e32 v3, s4
	global_load_dwordx2 v[2:3], v[2:3], off offset:248
	s_waitcnt vmcnt(0) lgkmcnt(0)
	v_mov_b32_e32 v0, s64
	v_readfirstlane_b32 s1, v4
	v_readfirstlane_b32 s4, v5
	v_mov_b32_e32 v6, s65
	v_mov_b32_e32 v4, s1
	v_mov_b32_e32 v5, s4
	v_mov_b32_e32 v4, v2
	v_mov_b32_e32 v5, v3
	v_mov_b32_e32 v34, v247
	v_readfirstlane_b32 s5, v3
	s_mov_b32 s15, s19
	s_mov_b32 s9, s19
	v_mov_b32_e32 v53, v1
	v_mov_b32_e32 v31, v1
	v_mov_b32_e32 v68, 0xf149f2ca
	s_waitcnt vmcnt(0) lgkmcnt(0)
	v_mov_b32_e32 v8, v5
	s_nop 0
	v_readfirstlane_b32 s1, v0
	v_readfirstlane_b32 s4, v6
	v_readfirstlane_b32 s20, v4
	v_mov_b32_e32 v6, s1
	v_mov_b32_e32 v7, s4
	s_add_i32 s1, s40, 0xe0
	v_readfirstlane_b32 s4, v2
	v_mov_b32_e32 v50, v2
	v_mov_b32_e32 v51, v3
	s_add_u32 s12, s4, 0x9f00000
	s_addc_u32 s13, s5, 0
	s_bfe_u32 s5, s1, 0x20004
	s_lshr_b32 s18, s1, 6
	s_lshl_b32 s1, s1, 1
	s_waitcnt vmcnt(0) lgkmcnt(0)
	s_lshl_b64 s[6:7], s[18:19], 11
	v_ashrrev_i32_e32 v0, 2, v34
	v_and_b32_e32 v35, 15, v34
	s_and_b32 s4, s1, 64
	s_lshl_b32 s1, s18, 8
	v_readfirstlane_b32 s21, v8
	v_lshrrev_b32_e32 v4, 1, v34
	v_ashrrev_i32_e32 v54, 3, v34
	v_and_b32_e32 v8, -16, v0
	v_or_b32_e32 v10, s0, v35
	v_mov_b32_e32 v5, s7
	s_add_i32 s18, s1, 0x4000
	v_and_b32_e32 v0, 24, v4
	v_ashrrev_i32_e32 v55, 31, v54
	v_add_u32_e32 v12, s4, v54
	v_ashrrev_i32_e32 v9, 31, v8
	v_or_b32_e32 v4, s6, v10
	v_mov_b64_e32 v[2:3], s[12:13]
	v_mov_b32_e32 v6, s20
	v_mov_b32_e32 v7, s21
	v_lshl_add_u64 v[10:11], s[18:19], 0, v[54:55]
	v_add_u32_e32 v12, 0x180, v12
	v_lshl_add_u64 v[56:57], v[4:5], 0, v[8:9]
	v_lshlrev_b32_e32 v36, 3, v34
	v_mad_u64_u32 v[4:5], s[20:21], v10, s2, v[2:3]
	v_mad_i64_i32 v[6:7], s[20:21], v12, s33, v[6:7]
	v_mad_u64_u32 v[2:3], s[20:21], v56, s2, v[2:3]
	s_lshl_b32 s14, s5, 7
	s_lshl_b32 s8, s4, 1
	v_and_b32_e32 v64, 56, v36
	v_mad_i32_i24 v5, v11, s2, v5
	s_mov_b64 s[20:21], 0x17700000
	v_mad_i32_i24 v3, v57, s2, v3
	v_lshlrev_b32_e32 v52, 1, v0
	v_lshlrev_b32_e32 v30, 1, v64
	v_lshl_add_u64 v[32:33], v[6:7], 0, s[20:21]
	v_lshl_add_u64 v[4:5], v[4:5], 0, s[8:9]
	v_lshl_add_u64 v[2:3], v[2:3], 0, s[14:15]
	v_lshl_add_u64 v[6:7], s[18:19], 1, v[32:33]
	v_lshl_add_u64 v[4:5], v[4:5], 0, v[30:31]
	v_lshl_add_u64 v[2:3], v[2:3], 0, v[52:53]
	v_lshl_add_u64 v[6:7], v[6:7], 0, v[30:31]
	global_load_dwordx4 v[22:25], v[4:5], off offset:2304
	global_load_dwordx4 v[26:29], v[6:7], off
	global_load_dwordx4 v[14:17], v[2:3], off offset:1792
	global_load_dwordx4 v[18:21], v[2:3], off offset:1856
	s_movk_i32 s9, 0x90
	v_lshlrev_b32_e32 v37, 4, v34
	v_lshlrev_b32_e32 v34, 1, v34
	v_mul_lo_u32 v38, v54, s9
	v_mov_b32_e32 v4, v1
	v_mov_b32_e32 v5, v1
	v_and_b32_e32 v36, 32, v36
	v_and_b32_e32 v37, 16, v37
	v_and_b32_e32 v34, 4, v34
	v_add_u32_e32 v67, 16, v38
	v_mov_b32_e32 v2, v1
	v_mov_b32_e32 v3, v1
	v_mov_b64_e32 v[8:9], v[4:5]
	v_mov_b64_e32 v[12:13], v[4:5]
	v_mul_u32_u24_e32 v65, 0x90, v35
	v_or3_b32 v66, v36, v37, v34
	v_add_u32_e32 v36, v67, v30
	v_lshl_add_u64 v[34:35], s[12:13], 0, v[30:31]
	v_lshl_add_u64 v[58:59], v[32:33], 0, v[30:31]
	s_or_b32 s18, s8, 0x900
	v_mov_b64_e32 v[32:33], v[4:5]
	s_mov_b32 s4, 0
	v_mov_b32_e32 v53, 0
	s_movk_i32 s14, 0x4040
	v_mov_b64_e32 v[6:7], v[2:3]
	v_mov_b64_e32 v[10:11], v[2:3]
	s_lshl_b32 s5, s5, 6
	v_lshl_add_u32 v37, v66, 1, v67
	v_lshl_add_u64 v[60:61], v[34:35], 0, s[18:19]
	v_mov_b64_e32 v[30:31], v[2:3]
	v_add_u32_e32 v37, 0x2000, v37
	s_waitcnt vmcnt(0) lgkmcnt(0)
	ds_write_b128 v36, v[22:25]
	ds_write2_b64 v37, v[26:27], v[28:29] offset0:128 offset1:130
	s_waitcnt lgkmcnt(0)
	s_barrier
	s_branch .LBB0_904

.LBB0_910:
	ds_bpermute_b32 v14, v63, v53
	s_lshl_b32 s18, s5, 1
	v_readfirstlane_b32 s6, v50
	v_readfirstlane_b32 s7, v51
	s_cmpk_gt_i32 s40, 0xaf
	s_waitcnt lgkmcnt(0)
	v_add_f32_e32 v16, v53, v14
	ds_bpermute_b32 v17, v62, v16
	v_lshlrev_b64 v[14:15], 11, v[56:57]
	v_lshl_add_u64 v[14:15], s[6:7], 0, v[14:15]
	v_lshl_add_u64 v[14:15], v[14:15], 0, s[18:19]
	v_lshl_add_u64 v[14:15], v[14:15], 0, v[0:1]
	s_waitcnt lgkmcnt(0)
	v_add_f32_e32 v16, v16, v17
	v_div_scale_f32 v17, s[4:5], v16, v16, 1.0
	v_rcp_f32_e32 v18, v17
	v_div_scale_f32 v0, vcc, 1.0, v16, 1.0
	s_mov_b64 s[4:5], 0x1e300400
	v_fma_f32 v19, -v17, v18, 1.0
	v_fmac_f32_e32 v18, v19, v18
	v_mul_f32_e32 v19, v0, v18
	v_fma_f32 v20, -v17, v19, v0
	v_fmac_f32_e32 v19, v20, v18
	v_fma_f32 v0, -v17, v19, v0
	v_div_fmas_f32 v0, v0, v18, v19
	v_div_fixup_f32 v0, v0, v16, 1.0
	v_lshl_add_u64 v[16:17], v[14:15], 0, s[4:5]
	v_pk_mul_f32 v[18:19], v[30:31], v[0:1] op_sel_hi:[1,0]
	v_pk_mul_f32 v[20:21], v[32:33], v[0:1] op_sel_hi:[1,0]
	v_add_co_u32_e32 v14, vcc, s34, v14
	v_pk_mul_f32 v[10:11], v[10:11], v[0:1] op_sel_hi:[1,0]
	v_pk_mul_f32 v[12:13], v[12:13], v[0:1] op_sel_hi:[1,0]
	v_pk_mul_f32 v[6:7], v[6:7], v[0:1] op_sel_hi:[1,0]
	v_pk_mul_f32 v[8:9], v[8:9], v[0:1] op_sel_hi:[1,0]
	v_pk_mul_f32 v[2:3], v[2:3], v[0:1] op_sel_hi:[1,0]
	v_pk_mul_f32 v[4:5], v[4:5], v[0:1] op_sel_hi:[1,0]
	v_cvt_pk_bf16_f32 v18, v18, v19
	v_cvt_pk_bf16_f32 v19, v20, v21
	v_addc_co_u32_e32 v15, vcc, 0, v15, vcc
	v_cvt_pk_bf16_f32 v10, v10, v11
	v_cvt_pk_bf16_f32 v11, v12, v13
	v_cvt_pk_bf16_f32 v6, v6, v7
	v_cvt_pk_bf16_f32 v7, v8, v9
	v_cvt_pk_bf16_f32 v2, v2, v3
	v_cvt_pk_bf16_f32 v3, v4, v5
	s_mov_b64 s[6:7], 0
	s_mov_b64 s[8:9], 0
	global_store_dwordx2 v[14:15], v[18:19], off offset:1024
	global_store_dwordx2 v[16:17], v[10:11], off offset:32
	global_store_dwordx2 v[16:17], v[6:7], off offset:64
	global_store_dwordx2 v[16:17], v[2:3], off offset:96
	s_cbranch_scc1 .LBB0_920
	v_mov_b32_e32 v2, s65
	v_mov_b32_e32 v3, s64
	v_mov_b32_e32 v4, s65
	v_readfirstlane_b32 s1, v3
	v_readfirstlane_b32 s4, v2
	v_mov_b32_e32 v5, s64
	v_mov_b32_e32 v2, s1
	v_mov_b32_e32 v3, s4
	global_load_dwordx2 v[2:3], v[2:3], off offset:248
	s_waitcnt vmcnt(0) lgkmcnt(0)
	v_mov_b32_e32 v0, s64
	v_readfirstlane_b32 s1, v5
	v_readfirstlane_b32 s4, v4
	v_mov_b32_e32 v6, s65
	v_mov_b32_e32 v4, s1
	v_mov_b32_e32 v5, s4
	v_mov_b32_e32 v4, v2
	v_mov_b32_e32 v5, v3
	s_waitcnt vmcnt(0) lgkmcnt(0)
	v_readfirstlane_b32 s8, v2
	v_readfirstlane_b32 s1, v0
	v_readfirstlane_b32 s4, v6
	v_mov_b32_e32 v60, v247
	v_mov_b32_e32 v6, s1
	v_mov_b32_e32 v7, s4
	v_mov_b32_e32 v50, v2
	v_mov_b32_e32 v51, v3
	v_readfirstlane_b32 s9, v3
	s_add_u32 s4, s8, 0x9f00000
	s_addc_u32 s5, s9, 0
	s_waitcnt vmcnt(0) lgkmcnt(0)
	v_mov_b64_e32 v[2:3], s[4:5]
	v_ashrrev_i32_e32 v0, 2, v60
	v_and_b32_e32 v14, 15, v60
	v_lshlrev_b32_e32 v15, 3, v60
	v_readfirstlane_b32 s4, v4
	v_readfirstlane_b32 s5, v5
	v_lshrrev_b32_e32 v7, 1, v60
	v_ashrrev_i32_e32 v54, 3, v60
	v_and_b32_e32 v6, -16, v0
	v_or_b32_e32 v0, s0, v14
	v_and_b32_e32 v61, 56, v15
	v_mov_b32_e32 v11, v1
	v_mov_b32_e32 v4, s4
	v_mov_b32_e32 v5, s5
	v_and_b32_e32 v12, 24, v7
	v_mad_i64_i32 v[8:9], s[4:5], v54, s2, v[2:3]
	v_add_u32_e32 v13, 0x1c0, v54
	v_ashrrev_i32_e32 v7, 31, v6
	v_or_b32_e32 v0, 0x3800, v0
	v_lshlrev_b32_e32 v10, 1, v61
	s_mov_b32 s12, 0xd500000
	s_lshl_b32 s1, s40, 2
	v_mad_i64_i32 v[4:5], s[4:5], v13, s33, v[4:5]
	v_lshl_add_u64 v[52:53], v[0:1], 0, v[6:7]
	v_lshl_add_u64 v[6:7], v[8:9], 0, v[10:11]
	s_add_i32 s1, s1, 64
	v_lshlrev_b32_e32 v0, 1, v12
	v_lshl_add_u64 v[12:13], v[4:5], 0, v[10:11]
	v_add_co_u32_e32 v4, vcc, s12, v6
	s_mov_b32 s13, 0x17708000
	s_and_b32 s1, s1, 0xc0
	v_addc_co_u32_e32 v5, vcc, 0, v7, vcc
	s_lshl_b32 s18, s1, 1
	v_add_co_u32_e32 v6, vcc, s13, v12
	v_mad_i64_i32 v[2:3], s[4:5], v52, s2, v[2:3]
	s_nop 0
	v_addc_co_u32_e32 v7, vcc, 0, v13, vcc
	global_load_dwordx4 v[26:29], v[4:5], off offset:2432
	global_load_dwordx4 v[30:33], v[6:7], off offset:3584
	v_lshl_add_u64 v[2:3], v[2:3], 0, s[18:19]
	v_lshl_add_u64 v[2:3], v[2:3], 0, v[0:1]
	global_load_dwordx4 v[18:21], v[2:3], off offset:1792
	global_load_dwordx4 v[22:25], v[2:3], off offset:1856
	v_lshlrev_b32_e32 v16, 4, v60
	v_lshlrev_b32_e32 v17, 1, v60
	s_movk_i32 s5, 0x90
	v_and_b32_e32 v15, 32, v15
	v_and_b32_e32 v16, 16, v16
	v_and_b32_e32 v17, 4, v17
	v_mul_lo_u32 v34, v54, s5
	v_or3_b32 v66, v15, v16, v17
	v_add_u32_e32 v67, 16, v34
	v_lshl_add_u32 v15, v66, 1, v67
	v_mov_b32_e32 v4, v1
	v_mov_b32_e32 v5, v1
	s_mov_b64 s[12:13], 0x9f00980
	v_mul_u32_u24_e32 v65, 0x90, v14
	v_add_u32_e32 v14, v67, v10
	v_lshl_add_u64 v[10:11], s[8:9], 0, v[10:11]
	v_add_u32_e32 v15, 0x2000, v15
	s_mov_b64 s[8:9], 0x17700000
	v_mov_b32_e32 v2, v1
	v_mov_b32_e32 v3, v1
	v_mov_b64_e32 v[8:9], v[4:5]
	v_lshl_add_u64 v[56:57], v[10:11], 0, s[12:13]
	v_lshl_add_u64 v[58:59], v[12:13], 0, s[8:9]
	s_waitcnt vmcnt(0) lgkmcnt(0)
	ds_write_b128 v14, v[26:29]
	ds_write2_b64 v15, v[30:31], v[32:33] offset0:128 offset1:130
	v_mov_b64_e32 v[12:13], v[4:5]
	v_mov_b64_e32 v[16:17], v[4:5]
	s_mov_b32 s0, 0
	v_mov_b32_e32 v68, 0xf149f2ca
	v_mov_b32_e32 v64, 0
	s_movk_i32 s4, 0x4040
	v_mov_b64_e32 v[6:7], v[2:3]
	v_ashrrev_i32_e32 v55, 31, v54
	v_mov_b64_e32 v[10:11], v[2:3]
	v_mov_b64_e32 v[14:15], v[2:3]
	s_waitcnt lgkmcnt(0)
	s_barrier
	s_branch .LBB0_913

.LBB0_968:
	s_branch .LBB0_979
	v_mov_b32_e32 v2, s64
	v_mov_b32_e32 v3, s65
	v_mov_b32_e32 v4, s64
	v_readfirstlane_b32 s0, v2
	v_readfirstlane_b32 s1, v3
	v_mov_b32_e32 v5, s65
	v_mov_b32_e32 v2, s0
	v_mov_b32_e32 v3, s1
	global_load_dwordx2 v[2:3], v[2:3], off offset:248
	s_waitcnt vmcnt(0) lgkmcnt(0)
	v_mov_b32_e32 v0, s64
	v_readfirstlane_b32 s0, v4
	v_readfirstlane_b32 s1, v5
	v_mov_b32_e32 v6, s65
	v_mov_b32_e32 v4, s0
	v_mov_b32_e32 v5, s1
	v_mov_b32_e32 v4, v2
	v_mov_b32_e32 v5, v3
	v_mov_b32_e32 v60, v247
	v_mov_b32_e32 v15, v1
	v_cmp_lt_i32_e32 vcc, v222, v220
	v_mov_b32_e32 v68, 0xf149f2ca
	v_mov_b32_e32 v62, 0
	s_waitcnt vmcnt(0) lgkmcnt(0)
	v_mov_b32_e32 v8, v5
	s_nop 0
	v_readfirstlane_b32 s0, v0
	v_readfirstlane_b32 s1, v6
	v_readfirstlane_b32 s13, v8
	v_mov_b32_e32 v6, s0
	v_readfirstlane_b32 s0, v2
	v_mov_b32_e32 v7, s1
	v_readfirstlane_b32 s1, v3
	s_add_u32 s8, s0, 0x9f00000
	v_mov_b32_e32 v50, v2
	v_mov_b32_e32 v51, v3
	s_addc_u32 s9, s1, 0
	s_ashr_i32 s4, s40, 6
	s_lshl_b32 s0, s40, 7
	s_lshl_b32 s6, s40, 1
	s_ashr_i32 s5, s4, 31
	s_and_b32 s12, s0, 0x780
	s_waitcnt vmcnt(0) lgkmcnt(0)
	s_and_b32 s14, s6, 64
	v_ashrrev_i32_e32 v0, 2, v60
	v_and_b32_e32 v34, 15, v60
	s_lshl_b64 s[6:7], s[4:5], 11
	v_ashrrev_i32_e32 v52, 3, v60
	v_and_b32_e32 v8, -16, v0
	v_or_b32_e32 v0, s12, v34
	v_mov_b32_e32 v5, s7
	v_readfirstlane_b32 s5, v4
	v_add_u32_e32 v11, s14, v52
	v_ashrrev_i32_e32 v9, 31, v8
	v_or_b32_e32 v4, s6, v0
	v_mov_b64_e32 v[2:3], s[8:9]
	v_mov_b32_e32 v6, s5
	v_mov_b32_e32 v7, s13
	v_add_u32_e32 v0, 0x180, v11
	v_lshl_add_u64 v[54:55], v[4:5], 0, v[8:9]
	s_bfe_u32 s1, s40, 0x20004
	v_mad_i64_i32 v[4:5], s[12:13], v0, s33, v[6:7]
	v_mad_u64_u32 v[6:7], s[12:13], v54, s2, v[2:3]
	s_lshl_b32 s0, s1, 6
	s_lshl_b32 s18, s1, 7
	s_lshl_b32 s1, s4, 8
	s_mov_b64 s[12:13], 0x17700000
	v_mad_i32_i24 v7, v55, s2, v7
	s_ashr_i32 s4, s1, 31
	v_lshl_add_u64 v[16:17], v[4:5], 0, s[12:13]
	v_lshl_add_u64 v[4:5], v[6:7], 0, s[18:19]
	s_lshl_b32 s18, s14, 1
	s_add_u32 s12, s1, 0x4000
	v_ashrrev_i32_e32 v53, 31, v52
	s_addc_u32 s13, s4, 0
	v_lshl_add_u64 v[6:7], s[12:13], 0, v[52:53]
	v_lshlrev_b32_e32 v35, 3, v60
	v_lshl_add_u64 v[8:9], s[12:13], 1, v[16:17]
	v_mad_u64_u32 v[2:3], s[12:13], v6, s2, v[2:3]
	v_lshrrev_b32_e32 v10, 1, v60
	v_and_b32_e32 v61, 56, v35
	v_mad_i32_i24 v3, v7, s2, v3
	v_lshlrev_b32_e32 v14, 1, v61
	v_lshl_add_u64 v[2:3], v[2:3], 0, s[18:19]
	v_and_b32_e32 v0, 24, v10
	v_lshl_add_u64 v[2:3], v[2:3], 0, v[14:15]
	v_lshlrev_b32_e32 v0, 1, v0
	v_lshl_add_u64 v[8:9], v[8:9], 0, v[14:15]
	global_load_dwordx4 v[30:33], v[2:3], off offset:2304
	v_lshl_add_u64 v[2:3], v[4:5], 0, v[0:1]
	global_load_dwordx4 v[26:29], v[8:9], off
	global_load_dwordx4 v[18:21], v[2:3], off offset:1792
	global_load_dwordx4 v[22:25], v[2:3], off offset:1856
	v_lshlrev_b32_e32 v36, 4, v60
	v_lshlrev_b32_e32 v37, 1, v60
	s_movk_i32 s13, 0x90
	v_cndmask_b32_e32 v6, v219, v222, vcc
	v_cmp_lt_i32_e32 vcc, v221, v220
	v_and_b32_e32 v35, 32, v35
	v_and_b32_e32 v36, 16, v36
	v_and_b32_e32 v37, 4, v37
	v_mul_lo_u32 v38, v52, s13
	v_cndmask_b32_e32 v7, v219, v221, vcc
	v_mov_b32_e32 v4, v1
	v_mov_b32_e32 v5, v1
	v_or3_b32 v66, v35, v36, v37
	v_add_u32_e32 v67, 16, v38
	v_mov_b32_e32 v2, v1
	v_mov_b32_e32 v3, v1
	v_lshlrev_b32_e32 v64, 2, v6
	v_lshlrev_b32_e32 v63, 2, v7
	v_mov_b64_e32 v[8:9], v[4:5]
	v_mov_b64_e32 v[12:13], v[4:5]
	v_mul_u32_u24_e32 v65, 0x90, v34
	v_add_u32_e32 v36, v67, v14
	v_lshl_add_u32 v37, v66, 1, v67
	v_lshl_add_u64 v[34:35], s[8:9], 0, v[14:15]
	v_lshl_add_u64 v[56:57], v[16:17], 0, v[14:15]
	s_or_b32 s18, s18, 0x900
	v_mov_b64_e32 v[16:17], v[4:5]
	s_mov_b32 s5, 0
	s_movk_i32 s12, 0x4040
	v_mov_b64_e32 v[6:7], v[2:3]
	v_mov_b64_e32 v[10:11], v[2:3]
	v_add_u32_e32 v37, 0x2000, v37
	v_lshl_add_u64 v[58:59], v[34:35], 0, s[18:19]
	v_mov_b64_e32 v[14:15], v[2:3]
	s_waitcnt vmcnt(0) lgkmcnt(0)
	ds_write2_b64 v37, v[26:27], v[28:29] offset0:128 offset1:130
	ds_write_b128 v36, v[30:33]
	s_waitcnt lgkmcnt(0)
	s_barrier
	s_branch .LBB0_970
